# post pass: each wave now takes two adjacent token rows per step (row pair 2w,2w+1) instead of rows 2048 apart
# speedup vs baseline: 1.0233x; 1.0019x over previous
.Lpost_setupdone:
	v_readfirstlane_b32 s0, v214
	s_nop 0
	s_lshl_b32 s0, s0, 1
	s_nop 0
.Lpost_loop:
	s_mov_b32 s2, 0
	s_cmp_ge_u32 s0, 8320
	s_addc_u32 s2, s2, 0
	s_cmp_ge_u32 s0, 16640
	s_addc_u32 s2, s2, 0
	s_cmp_ge_u32 s0, 24960
	s_addc_u32 s2, s2, 0
	s_mulk_i32 s2, 0x2080
	s_sub_u32 s18, s0, s2
	s_lshr_b32 s2, s2, 6
	s_mov_b32 s10, 0
	s_cmp_ge_u32 s0, 8320
	s_addc_u32 s10, s10, 0
	s_cmp_ge_u32 s0, 16640
	s_addc_u32 s10, s10, 0
	s_cmp_ge_u32 s0, 24960
	s_addc_u32 s10, s10, 0
	s_lshl_b32 s6, s0, 6
	s_lshl_b32 s2, s10, 13
	s_add_u32 s2, s2, s18
	s_sub_u32 s2, s2, 0x80
	s_mul_i32 s3, s10, s15
	s_add_u32 s3, s3, s18
	s_sub_u32 s3, s3, 0x70
	s_lshl_b32 s10, s10, 4
	s_add_u32 s10, s10, s18
	s_sub_u32 s10, s10, 0x70
	s_cmp_lt_u32 s18, 0x80
	s_cselect_b32 s74, s70, s68
	s_cselect_b32 s75, s71, s69
	s_cselect_b32 s3, s3, s2
	s_cselect_b32 s76, s62, s54
	s_cselect_b32 s77, s63, s55
	s_cselect_b32 s2, s10, s2
	s_lshl_b32 s3, s3, 12
	s_lshl_b32 s2, s2, 12
	s_add_u32 s74, s74, s3
	s_addc_u32 s75, s75, 0
	s_add_u32 s76, s76, s2
	s_addc_u32 s77, s77, 0
	v_add_u32_e32 v44, s6, v41
	v_add_u32_e32 v45, 0x1040000, v44
	v_add_u32_e32 v46, 0x2080000, v44
	v_add_u32_e32 v47, 0x30c0000, v44
	s_add_u32 s1, s0, 1
	s_mov_b32 s19, 0
	s_mov_b32 s82, 0
	s_cmp_ge_u32 s1, 33280
	s_cbranch_scc1 .Lpost_noB
	s_mov_b32 s82, 1
	s_mov_b32 s2, 0
	s_cmp_ge_u32 s1, 8320
	s_addc_u32 s2, s2, 0
	s_cmp_ge_u32 s1, 16640
	s_addc_u32 s2, s2, 0
	s_cmp_ge_u32 s1, 24960
	s_addc_u32 s2, s2, 0
	s_mulk_i32 s2, 0x2080
	s_sub_u32 s19, s1, s2
	s_lshr_b32 s2, s2, 6
	s_mov_b32 s10, 0
	s_cmp_ge_u32 s1, 8320
	s_addc_u32 s10, s10, 0
	s_cmp_ge_u32 s1, 16640
	s_addc_u32 s10, s10, 0
	s_cmp_ge_u32 s1, 24960
	s_addc_u32 s10, s10, 0
	s_lshl_b32 s7, s1, 6
	s_lshl_b32 s2, s10, 13
	s_add_u32 s2, s2, s19
	s_sub_u32 s2, s2, 0x80
	s_mul_i32 s3, s10, s15
	s_add_u32 s3, s3, s19
	s_sub_u32 s3, s3, 0x70
	s_lshl_b32 s10, s10, 4
	s_add_u32 s10, s10, s19
	s_sub_u32 s10, s10, 0x70
	s_cmp_lt_u32 s19, 0x80
	s_cselect_b32 s78, s70, s68
	s_cselect_b32 s79, s71, s69
	s_cselect_b32 s3, s3, s2
	s_cselect_b32 s80, s62, s54
	s_cselect_b32 s81, s63, s55
	s_cselect_b32 s2, s10, s2
	s_lshl_b32 s3, s3, 12
	s_lshl_b32 s2, s2, 12
	s_add_u32 s78, s78, s3
	s_addc_u32 s79, s79, 0
	s_add_u32 s80, s80, s2
	s_addc_u32 s81, s81, 0
	v_add_u32_e32 v48, s7, v41
	v_add_u32_e32 v49, 0x1040000, v48
	v_add_u32_e32 v50, 0x2080000, v48
	v_add_u32_e32 v51, 0x30c0000, v48

.Lpost_next:
	s_add_u32 s0, s1, 0xfff
	s_cmp_lt_u32 s0, 33280
	s_cbranch_scc1 .Lpost_loop
